# gate: head block means loaded and split to bf16 hi/lo once per phase into registers; item score tiles are 32 MFMAs
# speedup vs baseline: 1.0117x; 1.0008x over previous
.LBB0_267:
	s_and_b64 vcc, exec, s[6:7]
	s_cbranch_vccz .LBB0_503
	s_waitcnt vmcnt(0)
	v_mov_b32_e32 v40, v156
	s_mov_b32 s39, s79
	s_cmpk_gt_i32 s39, 0x3ff
	s_cbranch_scc1 .LBB0_503
	s_load_dwordx2 s[8:9], s[92:93], 0xa8
	s_waitcnt vmcnt(7)
	v_bfe_u32 v3, v40, 4, 2
	v_lshlrev_b32_e32 v158, 4, v3
	s_add_u32 s24, s90, 0x4940000
	v_ashrrev_i32_e32 v0, 2, v40
	s_waitcnt lgkmcnt(0)
	v_lshl_add_u64 v[32:33], s[8:9], 0, v[158:159]
	v_lshlrev_b32_e32 v158, 5, v3
	s_addc_u32 s25, s91, 0
	v_and_b32_e32 v2, 15, v40
	v_bfi_b32 v42, -16, v0, v40
	v_lshl_add_u64 v[0:1], s[90:91], 0, v[158:159]
	s_mov_b64 s[0:1], 0x4900000
	s_add_u32 s88, s90, 0xec00000
	v_lshl_add_u64 v[34:35], v[0:1], 0, s[0:1]
	v_lshlrev_b32_e32 v46, 2, v3
	v_lshlrev_b32_e32 v0, 7, v2
	s_addc_u32 s89, s91, 0
	v_cmp_gt_i32_e64 s[6:7], 64, v40
	v_lshl_add_u32 v41, v40, 2, 0
	v_or_b32_e32 v43, 0x3e8, v3
	v_or_b32_e32 v44, 0x7d0, v3
	v_or_b32_e32 v45, 0xbb8, v3
	v_cmp_eq_u32_e64 s[8:9], 0, v3
	v_or_b32_e32 v47, 1, v46
	v_or_b32_e32 v48, 2, v46
	v_or_b32_e32 v49, 3, v46
	v_or_b32_e32 v50, 16, v46
	v_or_b32_e32 v51, 17, v46
	s_waitcnt vmcnt(6)
	v_or_b32_e32 v52, 18, v46
	v_or_b32_e32 v53, 19, v46
	v_or_b32_e32 v54, 32, v46
	v_or_b32_e32 v55, 33, v46
	s_waitcnt vmcnt(0)
	v_or_b32_e32 v56, 34, v46
	v_or_b32_e32 v57, 35, v46
	v_or_b32_e32 v58, 48, v46
	v_or_b32_e32 v59, 49, v46
	v_or_b32_e32 v60, 50, v46
	v_or_b32_e32 v61, 51, v46
	s_lshl_b32 s47, s39, 4
	v_lshlrev_b32_e32 v62, 2, v0
	s_and_b32 s0, s39, 7
	v_lshl_or_b32 v158, s0, 15, v62
	v_lshl_add_u64 v[202:203], v[34:35], 0, v[158:159]
	global_load_dwordx4 v[0:3], v[202:203], off
	global_load_dwordx4 v[4:7], v[202:203], off offset:16
	global_load_dwordx4 v[8:11], v[202:203], off offset:128
	global_load_dwordx4 v[12:15], v[202:203], off offset:144
	global_load_dwordx4 v[16:19], v[202:203], off offset:256
	global_load_dwordx4 v[20:23], v[202:203], off offset:272
	global_load_dwordx4 v[24:27], v[202:203], off offset:384
	global_load_dwordx4 v[28:31], v[202:203], off offset:400
	s_waitcnt vmcnt(6)
	v_cvt_pk_bf16_f32 v76, v0, v1
	v_cvt_pk_bf16_f32 v77, v2, v3
	v_cvt_pk_bf16_f32 v78, v4, v5
	v_cvt_pk_bf16_f32 v79, v6, v7
	v_lshlrev_b32_e32 v190, 16, v76
	v_and_b32_e32 v191, 0xffff0000, v76
	v_sub_f32_e32 v190, v0, v190
	v_sub_f32_e32 v191, v1, v191
	v_cvt_pk_bf16_f32 v80, v190, v191
	v_lshlrev_b32_e32 v190, 16, v77
	v_and_b32_e32 v191, 0xffff0000, v77
	v_sub_f32_e32 v190, v2, v190
	v_sub_f32_e32 v191, v3, v191
	v_cvt_pk_bf16_f32 v81, v190, v191
	v_lshlrev_b32_e32 v190, 16, v78
	v_and_b32_e32 v191, 0xffff0000, v78
	v_sub_f32_e32 v190, v4, v190
	v_sub_f32_e32 v191, v5, v191
	v_cvt_pk_bf16_f32 v82, v190, v191
	v_lshlrev_b32_e32 v190, 16, v79
	v_and_b32_e32 v191, 0xffff0000, v79
	v_sub_f32_e32 v190, v6, v190
	v_sub_f32_e32 v191, v7, v191
	v_cvt_pk_bf16_f32 v83, v190, v191
	s_waitcnt vmcnt(4)
	v_cvt_pk_bf16_f32 v84, v8, v9
	v_cvt_pk_bf16_f32 v85, v10, v11
	v_cvt_pk_bf16_f32 v86, v12, v13
	v_cvt_pk_bf16_f32 v87, v14, v15
	v_lshlrev_b32_e32 v190, 16, v84
	v_and_b32_e32 v191, 0xffff0000, v84
	v_sub_f32_e32 v190, v8, v190
	v_sub_f32_e32 v191, v9, v191
	v_cvt_pk_bf16_f32 v88, v190, v191
	v_lshlrev_b32_e32 v190, 16, v85
	v_and_b32_e32 v191, 0xffff0000, v85
	v_sub_f32_e32 v190, v10, v190
	v_sub_f32_e32 v191, v11, v191
	v_cvt_pk_bf16_f32 v89, v190, v191
	v_lshlrev_b32_e32 v190, 16, v86
	v_and_b32_e32 v191, 0xffff0000, v86
	v_sub_f32_e32 v190, v12, v190
	v_sub_f32_e32 v191, v13, v191
	v_cvt_pk_bf16_f32 v90, v190, v191
	v_lshlrev_b32_e32 v190, 16, v87
	v_and_b32_e32 v191, 0xffff0000, v87
	v_sub_f32_e32 v190, v14, v190
	v_sub_f32_e32 v191, v15, v191
	v_cvt_pk_bf16_f32 v91, v190, v191
	s_waitcnt vmcnt(2)
	v_cvt_pk_bf16_f32 v92, v16, v17
	v_cvt_pk_bf16_f32 v93, v18, v19
	v_cvt_pk_bf16_f32 v94, v20, v21
	v_cvt_pk_bf16_f32 v95, v22, v23
	v_lshlrev_b32_e32 v190, 16, v92
	v_and_b32_e32 v191, 0xffff0000, v92
	v_sub_f32_e32 v190, v16, v190
	v_sub_f32_e32 v191, v17, v191
	v_cvt_pk_bf16_f32 v96, v190, v191
	v_lshlrev_b32_e32 v190, 16, v93
	v_and_b32_e32 v191, 0xffff0000, v93
	v_sub_f32_e32 v190, v18, v190
	v_sub_f32_e32 v191, v19, v191
	v_cvt_pk_bf16_f32 v97, v190, v191
	v_lshlrev_b32_e32 v190, 16, v94
	v_and_b32_e32 v191, 0xffff0000, v94
	v_sub_f32_e32 v190, v20, v190
	v_sub_f32_e32 v191, v21, v191
	v_cvt_pk_bf16_f32 v98, v190, v191
	v_lshlrev_b32_e32 v190, 16, v95
	v_and_b32_e32 v191, 0xffff0000, v95
	v_sub_f32_e32 v190, v22, v190
	v_sub_f32_e32 v191, v23, v191
	v_cvt_pk_bf16_f32 v99, v190, v191
	s_waitcnt vmcnt(0)
	v_cvt_pk_bf16_f32 v100, v24, v25
	v_cvt_pk_bf16_f32 v101, v26, v27
	v_cvt_pk_bf16_f32 v102, v28, v29
	v_cvt_pk_bf16_f32 v103, v30, v31
	v_lshlrev_b32_e32 v190, 16, v100
	v_and_b32_e32 v191, 0xffff0000, v100
	v_sub_f32_e32 v190, v24, v190
	v_sub_f32_e32 v191, v25, v191
	v_cvt_pk_bf16_f32 v104, v190, v191
	v_lshlrev_b32_e32 v190, 16, v101
	v_and_b32_e32 v191, 0xffff0000, v101
	v_sub_f32_e32 v190, v26, v190
	v_sub_f32_e32 v191, v27, v191
	v_cvt_pk_bf16_f32 v105, v190, v191
	v_lshlrev_b32_e32 v190, 16, v102
	v_and_b32_e32 v191, 0xffff0000, v102
	v_sub_f32_e32 v190, v28, v190
	v_sub_f32_e32 v191, v29, v191
	v_cvt_pk_bf16_f32 v106, v190, v191
	v_lshlrev_b32_e32 v190, 16, v103
	v_and_b32_e32 v191, 0xffff0000, v103
	v_sub_f32_e32 v190, v30, v190
	v_sub_f32_e32 v191, v31, v191
	v_cvt_pk_bf16_f32 v107, v190, v191
	s_mov_b64 s[10:11], 0x2000
	v_lshl_add_u64 v[204:205], v[202:203], 0, s[10:11]
	global_load_dwordx4 v[0:3], v[204:205], off
	global_load_dwordx4 v[4:7], v[204:205], off offset:16
	global_load_dwordx4 v[8:11], v[204:205], off offset:128
	global_load_dwordx4 v[12:15], v[204:205], off offset:144
	global_load_dwordx4 v[16:19], v[204:205], off offset:256
	global_load_dwordx4 v[20:23], v[204:205], off offset:272
	global_load_dwordx4 v[24:27], v[204:205], off offset:384
	global_load_dwordx4 v[28:31], v[204:205], off offset:400
	s_waitcnt vmcnt(6)
	v_cvt_pk_bf16_f32 v108, v0, v1
	v_cvt_pk_bf16_f32 v109, v2, v3
	v_cvt_pk_bf16_f32 v110, v4, v5
	v_cvt_pk_bf16_f32 v111, v6, v7
	v_lshlrev_b32_e32 v190, 16, v108
	v_and_b32_e32 v191, 0xffff0000, v108
	v_sub_f32_e32 v190, v0, v190
	v_sub_f32_e32 v191, v1, v191
	v_cvt_pk_bf16_f32 v112, v190, v191
	v_lshlrev_b32_e32 v190, 16, v109
	v_and_b32_e32 v191, 0xffff0000, v109
	v_sub_f32_e32 v190, v2, v190
	v_sub_f32_e32 v191, v3, v191
	v_cvt_pk_bf16_f32 v113, v190, v191
	v_lshlrev_b32_e32 v190, 16, v110
	v_and_b32_e32 v191, 0xffff0000, v110
	v_sub_f32_e32 v190, v4, v190
	v_sub_f32_e32 v191, v5, v191
	v_cvt_pk_bf16_f32 v114, v190, v191
	v_lshlrev_b32_e32 v190, 16, v111
	v_and_b32_e32 v191, 0xffff0000, v111
	v_sub_f32_e32 v190, v6, v190
	v_sub_f32_e32 v191, v7, v191
	v_cvt_pk_bf16_f32 v115, v190, v191
	s_waitcnt vmcnt(4)
	v_cvt_pk_bf16_f32 v116, v8, v9
	v_cvt_pk_bf16_f32 v117, v10, v11
	v_cvt_pk_bf16_f32 v118, v12, v13
	v_cvt_pk_bf16_f32 v119, v14, v15
	v_lshlrev_b32_e32 v190, 16, v116
	v_and_b32_e32 v191, 0xffff0000, v116
	v_sub_f32_e32 v190, v8, v190
	v_sub_f32_e32 v191, v9, v191
	v_cvt_pk_bf16_f32 v120, v190, v191
	v_lshlrev_b32_e32 v190, 16, v117
	v_and_b32_e32 v191, 0xffff0000, v117
	v_sub_f32_e32 v190, v10, v190
	v_sub_f32_e32 v191, v11, v191
	v_cvt_pk_bf16_f32 v121, v190, v191
	v_lshlrev_b32_e32 v190, 16, v118
	v_and_b32_e32 v191, 0xffff0000, v118
	v_sub_f32_e32 v190, v12, v190
	v_sub_f32_e32 v191, v13, v191
	v_cvt_pk_bf16_f32 v122, v190, v191
	v_lshlrev_b32_e32 v190, 16, v119
	v_and_b32_e32 v191, 0xffff0000, v119
	v_sub_f32_e32 v190, v14, v190
	v_sub_f32_e32 v191, v15, v191
	v_cvt_pk_bf16_f32 v123, v190, v191
	s_waitcnt vmcnt(2)
	v_cvt_pk_bf16_f32 v124, v16, v17
	v_cvt_pk_bf16_f32 v125, v18, v19
	v_cvt_pk_bf16_f32 v126, v20, v21
	v_cvt_pk_bf16_f32 v127, v22, v23
	v_lshlrev_b32_e32 v190, 16, v124
	v_and_b32_e32 v191, 0xffff0000, v124
	v_sub_f32_e32 v190, v16, v190
	v_sub_f32_e32 v191, v17, v191
	v_cvt_pk_bf16_f32 v128, v190, v191
	v_lshlrev_b32_e32 v190, 16, v125
	v_and_b32_e32 v191, 0xffff0000, v125
	v_sub_f32_e32 v190, v18, v190
	v_sub_f32_e32 v191, v19, v191
	v_cvt_pk_bf16_f32 v129, v190, v191
	v_lshlrev_b32_e32 v190, 16, v126
	v_and_b32_e32 v191, 0xffff0000, v126
	v_sub_f32_e32 v190, v20, v190
	v_sub_f32_e32 v191, v21, v191
	v_cvt_pk_bf16_f32 v130, v190, v191
	v_lshlrev_b32_e32 v190, 16, v127
	v_and_b32_e32 v191, 0xffff0000, v127
	v_sub_f32_e32 v190, v22, v190
	v_sub_f32_e32 v191, v23, v191
	v_cvt_pk_bf16_f32 v131, v190, v191
	s_waitcnt vmcnt(0)
	v_cvt_pk_bf16_f32 v132, v24, v25
	v_cvt_pk_bf16_f32 v133, v26, v27
	v_cvt_pk_bf16_f32 v134, v28, v29
	v_cvt_pk_bf16_f32 v135, v30, v31
	v_lshlrev_b32_e32 v190, 16, v132
	v_and_b32_e32 v191, 0xffff0000, v132
	v_sub_f32_e32 v190, v24, v190
	v_sub_f32_e32 v191, v25, v191
	v_cvt_pk_bf16_f32 v136, v190, v191
	v_lshlrev_b32_e32 v190, 16, v133
	v_and_b32_e32 v191, 0xffff0000, v133
	v_sub_f32_e32 v190, v26, v190
	v_sub_f32_e32 v191, v27, v191
	v_cvt_pk_bf16_f32 v137, v190, v191
	v_lshlrev_b32_e32 v190, 16, v134
	v_and_b32_e32 v191, 0xffff0000, v134
	v_sub_f32_e32 v190, v28, v190
	v_sub_f32_e32 v191, v29, v191
	v_cvt_pk_bf16_f32 v138, v190, v191
	v_lshlrev_b32_e32 v190, 16, v135
	v_and_b32_e32 v191, 0xffff0000, v135
	v_sub_f32_e32 v190, v30, v190
	v_sub_f32_e32 v191, v31, v191
	v_cvt_pk_bf16_f32 v139, v190, v191
	s_mov_b64 s[10:11], 0x4000
	v_lshl_add_u64 v[204:205], v[202:203], 0, s[10:11]
	global_load_dwordx4 v[0:3], v[204:205], off
	global_load_dwordx4 v[4:7], v[204:205], off offset:16
	global_load_dwordx4 v[8:11], v[204:205], off offset:128
	global_load_dwordx4 v[12:15], v[204:205], off offset:144
	global_load_dwordx4 v[16:19], v[204:205], off offset:256
	global_load_dwordx4 v[20:23], v[204:205], off offset:272
	global_load_dwordx4 v[24:27], v[204:205], off offset:384
	global_load_dwordx4 v[28:31], v[204:205], off offset:400
	s_waitcnt vmcnt(6)
	v_cvt_pk_bf16_f32 v140, v0, v1
	v_cvt_pk_bf16_f32 v141, v2, v3
	v_cvt_pk_bf16_f32 v142, v4, v5
	v_cvt_pk_bf16_f32 v143, v6, v7
	v_lshlrev_b32_e32 v190, 16, v140
	v_and_b32_e32 v191, 0xffff0000, v140
	v_sub_f32_e32 v190, v0, v190
	v_sub_f32_e32 v191, v1, v191
	v_cvt_pk_bf16_f32 v144, v190, v191
	v_lshlrev_b32_e32 v190, 16, v141
	v_and_b32_e32 v191, 0xffff0000, v141
	v_sub_f32_e32 v190, v2, v190
	v_sub_f32_e32 v191, v3, v191
	v_cvt_pk_bf16_f32 v145, v190, v191
	v_lshlrev_b32_e32 v190, 16, v142
	v_and_b32_e32 v191, 0xffff0000, v142
	v_sub_f32_e32 v190, v4, v190
	v_sub_f32_e32 v191, v5, v191
	v_cvt_pk_bf16_f32 v146, v190, v191
	v_lshlrev_b32_e32 v190, 16, v143
	v_and_b32_e32 v191, 0xffff0000, v143
	v_sub_f32_e32 v190, v6, v190
	v_sub_f32_e32 v191, v7, v191
	v_cvt_pk_bf16_f32 v147, v190, v191
	s_waitcnt vmcnt(4)
	v_cvt_pk_bf16_f32 v148, v8, v9
	v_cvt_pk_bf16_f32 v149, v10, v11
	v_cvt_pk_bf16_f32 v150, v12, v13
	v_cvt_pk_bf16_f32 v151, v14, v15
	v_lshlrev_b32_e32 v190, 16, v148
	v_and_b32_e32 v191, 0xffff0000, v148
	v_sub_f32_e32 v190, v8, v190
	v_sub_f32_e32 v191, v9, v191
	v_cvt_pk_bf16_f32 v152, v190, v191
	v_lshlrev_b32_e32 v190, 16, v149
	v_and_b32_e32 v191, 0xffff0000, v149
	v_sub_f32_e32 v190, v10, v190
	v_sub_f32_e32 v191, v11, v191
	v_cvt_pk_bf16_f32 v153, v190, v191
	v_lshlrev_b32_e32 v190, 16, v150
	v_and_b32_e32 v191, 0xffff0000, v150
	v_sub_f32_e32 v190, v12, v190
	v_sub_f32_e32 v191, v13, v191
	v_cvt_pk_bf16_f32 v154, v190, v191
	v_lshlrev_b32_e32 v190, 16, v151
	v_and_b32_e32 v191, 0xffff0000, v151
	v_sub_f32_e32 v190, v14, v190
	v_sub_f32_e32 v191, v15, v191
	v_cvt_pk_bf16_f32 v155, v190, v191
	s_waitcnt vmcnt(2)
	v_cvt_pk_bf16_f32 v166, v16, v17
	v_cvt_pk_bf16_f32 v167, v18, v19
	v_cvt_pk_bf16_f32 v168, v20, v21
	v_cvt_pk_bf16_f32 v169, v22, v23
	v_lshlrev_b32_e32 v190, 16, v166
	v_and_b32_e32 v191, 0xffff0000, v166
	v_sub_f32_e32 v190, v16, v190
	v_sub_f32_e32 v191, v17, v191
	v_cvt_pk_bf16_f32 v170, v190, v191
	v_lshlrev_b32_e32 v190, 16, v167
	v_and_b32_e32 v191, 0xffff0000, v167
	v_sub_f32_e32 v190, v18, v190
	v_sub_f32_e32 v191, v19, v191
	v_cvt_pk_bf16_f32 v171, v190, v191
	v_lshlrev_b32_e32 v190, 16, v168
	v_and_b32_e32 v191, 0xffff0000, v168
	v_sub_f32_e32 v190, v20, v190
	v_sub_f32_e32 v191, v21, v191
	v_cvt_pk_bf16_f32 v172, v190, v191
	v_lshlrev_b32_e32 v190, 16, v169
	v_and_b32_e32 v191, 0xffff0000, v169
	v_sub_f32_e32 v190, v22, v190
	v_sub_f32_e32 v191, v23, v191
	v_cvt_pk_bf16_f32 v173, v190, v191
	s_waitcnt vmcnt(0)
	v_cvt_pk_bf16_f32 v174, v24, v25
	v_cvt_pk_bf16_f32 v175, v26, v27
	v_cvt_pk_bf16_f32 v176, v28, v29
	v_cvt_pk_bf16_f32 v177, v30, v31
	v_lshlrev_b32_e32 v190, 16, v174
	v_and_b32_e32 v191, 0xffff0000, v174
	v_sub_f32_e32 v190, v24, v190
	v_sub_f32_e32 v191, v25, v191
	v_cvt_pk_bf16_f32 v178, v190, v191
	v_lshlrev_b32_e32 v190, 16, v175
	v_and_b32_e32 v191, 0xffff0000, v175
	v_sub_f32_e32 v190, v26, v190
	v_sub_f32_e32 v191, v27, v191
	v_cvt_pk_bf16_f32 v179, v190, v191
	v_lshlrev_b32_e32 v190, 16, v176
	v_and_b32_e32 v191, 0xffff0000, v176
	v_sub_f32_e32 v190, v28, v190
	v_sub_f32_e32 v191, v29, v191
	v_cvt_pk_bf16_f32 v180, v190, v191
	v_lshlrev_b32_e32 v190, 16, v177
	v_and_b32_e32 v191, 0xffff0000, v177
	v_sub_f32_e32 v190, v30, v190
	v_sub_f32_e32 v191, v31, v191
	v_cvt_pk_bf16_f32 v181, v190, v191
	s_mov_b64 s[10:11], 0x6000
	v_lshl_add_u64 v[204:205], v[202:203], 0, s[10:11]
	global_load_dwordx4 v[0:3], v[204:205], off
	global_load_dwordx4 v[4:7], v[204:205], off offset:16
	global_load_dwordx4 v[8:11], v[204:205], off offset:128
	global_load_dwordx4 v[12:15], v[204:205], off offset:144
	global_load_dwordx4 v[16:19], v[204:205], off offset:256
	global_load_dwordx4 v[20:23], v[204:205], off offset:272
	global_load_dwordx4 v[24:27], v[204:205], off offset:384
	global_load_dwordx4 v[28:31], v[204:205], off offset:400
	s_waitcnt vmcnt(6)
	v_cvt_pk_bf16_f32 v182, v0, v1
	v_cvt_pk_bf16_f32 v183, v2, v3
	v_cvt_pk_bf16_f32 v184, v4, v5
	v_cvt_pk_bf16_f32 v185, v6, v7
	v_lshlrev_b32_e32 v190, 16, v182
	v_and_b32_e32 v191, 0xffff0000, v182
	v_sub_f32_e32 v190, v0, v190
	v_sub_f32_e32 v191, v1, v191
	v_cvt_pk_bf16_f32 v186, v190, v191
	v_lshlrev_b32_e32 v190, 16, v183
	v_and_b32_e32 v191, 0xffff0000, v183
	v_sub_f32_e32 v190, v2, v190
	v_sub_f32_e32 v191, v3, v191
	v_cvt_pk_bf16_f32 v187, v190, v191
	v_lshlrev_b32_e32 v190, 16, v184
	v_and_b32_e32 v191, 0xffff0000, v184
	v_sub_f32_e32 v190, v4, v190
	v_sub_f32_e32 v191, v5, v191
	v_cvt_pk_bf16_f32 v188, v190, v191
	v_lshlrev_b32_e32 v190, 16, v185
	v_and_b32_e32 v191, 0xffff0000, v185
	v_sub_f32_e32 v190, v6, v190
	v_sub_f32_e32 v191, v7, v191
	v_cvt_pk_bf16_f32 v189, v190, v191
	s_waitcnt vmcnt(4)
	v_cvt_pk_bf16_f32 v214, v8, v9
	v_cvt_pk_bf16_f32 v215, v10, v11
	v_cvt_pk_bf16_f32 v216, v12, v13
	v_cvt_pk_bf16_f32 v217, v14, v15
	v_lshlrev_b32_e32 v190, 16, v214
	v_and_b32_e32 v191, 0xffff0000, v214
	v_sub_f32_e32 v190, v8, v190
	v_sub_f32_e32 v191, v9, v191
	v_cvt_pk_bf16_f32 v218, v190, v191
	v_lshlrev_b32_e32 v190, 16, v215
	v_and_b32_e32 v191, 0xffff0000, v215
	v_sub_f32_e32 v190, v10, v190
	v_sub_f32_e32 v191, v11, v191
	v_cvt_pk_bf16_f32 v219, v190, v191
	v_lshlrev_b32_e32 v190, 16, v216
	v_and_b32_e32 v191, 0xffff0000, v216
	v_sub_f32_e32 v190, v12, v190
	v_sub_f32_e32 v191, v13, v191
	v_cvt_pk_bf16_f32 v220, v190, v191
	v_lshlrev_b32_e32 v190, 16, v217
	v_and_b32_e32 v191, 0xffff0000, v217
	v_sub_f32_e32 v190, v14, v190
	v_sub_f32_e32 v191, v15, v191
	v_cvt_pk_bf16_f32 v221, v190, v191
	s_waitcnt vmcnt(2)
	v_cvt_pk_bf16_f32 v222, v16, v17
	v_cvt_pk_bf16_f32 v223, v18, v19
	v_cvt_pk_bf16_f32 v224, v20, v21
	v_cvt_pk_bf16_f32 v225, v22, v23
	v_lshlrev_b32_e32 v190, 16, v222
	v_and_b32_e32 v191, 0xffff0000, v222
	v_sub_f32_e32 v190, v16, v190
	v_sub_f32_e32 v191, v17, v191
	v_cvt_pk_bf16_f32 v226, v190, v191
	v_lshlrev_b32_e32 v190, 16, v223
	v_and_b32_e32 v191, 0xffff0000, v223
	v_sub_f32_e32 v190, v18, v190
	v_sub_f32_e32 v191, v19, v191
	v_cvt_pk_bf16_f32 v227, v190, v191
	v_lshlrev_b32_e32 v190, 16, v224
	v_and_b32_e32 v191, 0xffff0000, v224
	v_sub_f32_e32 v190, v20, v190
	v_sub_f32_e32 v191, v21, v191
	v_cvt_pk_bf16_f32 v228, v190, v191
	v_lshlrev_b32_e32 v190, 16, v225
	v_and_b32_e32 v191, 0xffff0000, v225
	v_sub_f32_e32 v190, v22, v190
	v_sub_f32_e32 v191, v23, v191
	v_cvt_pk_bf16_f32 v229, v190, v191
	s_waitcnt vmcnt(0)
	v_cvt_pk_bf16_f32 v230, v24, v25
	v_cvt_pk_bf16_f32 v231, v26, v27
	v_cvt_pk_bf16_f32 v232, v28, v29
	v_cvt_pk_bf16_f32 v233, v30, v31
	v_lshlrev_b32_e32 v190, 16, v230
	v_and_b32_e32 v191, 0xffff0000, v230
	v_sub_f32_e32 v190, v24, v190
	v_sub_f32_e32 v191, v25, v191
	v_cvt_pk_bf16_f32 v234, v190, v191
	v_lshlrev_b32_e32 v190, 16, v231
	v_and_b32_e32 v191, 0xffff0000, v231
	v_sub_f32_e32 v190, v26, v190
	v_sub_f32_e32 v191, v27, v191
	v_cvt_pk_bf16_f32 v235, v190, v191
	v_lshlrev_b32_e32 v190, 16, v232
	v_and_b32_e32 v191, 0xffff0000, v232
	v_sub_f32_e32 v190, v28, v190
	v_sub_f32_e32 v191, v29, v191
	v_cvt_pk_bf16_f32 v236, v190, v191
	v_lshlrev_b32_e32 v190, 16, v233
	v_and_b32_e32 v191, 0xffff0000, v233
	v_sub_f32_e32 v190, v30, v190
	v_sub_f32_e32 v191, v31, v191
	v_cvt_pk_bf16_f32 v237, v190, v191
	s_branch .LBB0_271

.LBB0_271:
	s_barrier
	s_and_saveexec_b64 s[10:11], s[6:7]
	ds_write_b32 v41, v159
	s_or_b64 exec, exec, s[10:11]
	s_and_b32 s0, s47, 0xffffff80
	s_and_b32 s72, s39, 7
	v_add_u32_e32 v36, s0, v42
	s_lshl_b32 s48, s72, 14
	v_ashrrev_i32_e32 v37, 31, v36
	v_lshl_add_u64 v[0:1], v[36:37], 0, s[48:49]
	v_lshlrev_b64 v[0:1], 8, v[0:1]
	v_lshl_add_u64 v[0:1], v[32:33], 0, v[0:1]
	s_waitcnt lgkmcnt(0)
	s_barrier
	global_load_dwordx4 v[20:23], v[0:1], off
	global_load_dwordx4 v[16:19], v[0:1], off offset:64
	global_load_dwordx4 v[12:15], v[0:1], off offset:128
	s_nop 0
	global_load_dwordx4 v[0:3], v[0:1], off offset:192
	s_ashr_i32 s48, s39, 4
	s_add_i32 s0, s48, 15
	s_ashr_i32 s0, s0, 4
	v_mov_b32_e32 v4, 0
	s_cmp_lt_i32 s0, 1
	v_lshl_or_b32 v158, s72, 15, v62
	v_mov_b32_e32 v8, 0
	v_mov_b32_e32 v9, 0
	v_mov_b32_e32 v10, 0
	v_mov_b32_e32 v11, 0
	s_cbranch_scc1 .LBB0_275
	s_waitcnt vmcnt(0)
	v_mfma_f32_16x16x32_bf16 v[8:11], v[76:79], v[20:23], 0
	v_mfma_f32_16x16x32_bf16 v[8:11], v[80:83], v[20:23], v[8:11]
	v_mfma_f32_16x16x32_bf16 v[8:11], v[84:87], v[16:19], v[8:11]
	v_mfma_f32_16x16x32_bf16 v[8:11], v[88:91], v[16:19], v[8:11]
	v_mfma_f32_16x16x32_bf16 v[8:11], v[92:95], v[12:15], v[8:11]
	v_mfma_f32_16x16x32_bf16 v[8:11], v[96:99], v[12:15], v[8:11]
	v_mfma_f32_16x16x32_bf16 v[8:11], v[100:103], v[0:3], v[8:11]
	v_mfma_f32_16x16x32_bf16 v[8:11], v[104:107], v[0:3], v[8:11]
	v_mfma_f32_16x16x32_bf16 v[4:7], v[108:111], v[20:23], 0
	v_mfma_f32_16x16x32_bf16 v[4:7], v[112:115], v[20:23], v[4:7]
	v_mfma_f32_16x16x32_bf16 v[4:7], v[116:119], v[16:19], v[4:7]
	v_mfma_f32_16x16x32_bf16 v[4:7], v[120:123], v[16:19], v[4:7]
	v_mfma_f32_16x16x32_bf16 v[4:7], v[124:127], v[12:15], v[4:7]
	v_mfma_f32_16x16x32_bf16 v[4:7], v[128:131], v[12:15], v[4:7]
	v_mfma_f32_16x16x32_bf16 v[4:7], v[132:135], v[0:3], v[4:7]
	v_mfma_f32_16x16x32_bf16 v[4:7], v[136:139], v[0:3], v[4:7]
	v_mfma_f32_16x16x32_bf16 v[28:31], v[140:143], v[20:23], 0
	v_mfma_f32_16x16x32_bf16 v[28:31], v[144:147], v[20:23], v[28:31]
	v_mfma_f32_16x16x32_bf16 v[28:31], v[148:151], v[16:19], v[28:31]
	v_mfma_f32_16x16x32_bf16 v[28:31], v[152:155], v[16:19], v[28:31]
	v_mfma_f32_16x16x32_bf16 v[28:31], v[166:169], v[12:15], v[28:31]
	v_mfma_f32_16x16x32_bf16 v[28:31], v[170:173], v[12:15], v[28:31]
	v_mfma_f32_16x16x32_bf16 v[28:31], v[174:177], v[0:3], v[28:31]
	v_mfma_f32_16x16x32_bf16 v[28:31], v[178:181], v[0:3], v[28:31]
	v_mfma_f32_16x16x32_bf16 v[24:27], v[182:185], v[20:23], 0
	v_mfma_f32_16x16x32_bf16 v[24:27], v[186:189], v[20:23], v[24:27]
	v_mfma_f32_16x16x32_bf16 v[24:27], v[214:217], v[16:19], v[24:27]
	v_mfma_f32_16x16x32_bf16 v[24:27], v[218:221], v[16:19], v[24:27]
	v_mfma_f32_16x16x32_bf16 v[24:27], v[222:225], v[12:15], v[24:27]
	v_mfma_f32_16x16x32_bf16 v[24:27], v[226:229], v[12:15], v[24:27]
	v_mfma_f32_16x16x32_bf16 v[24:27], v[230:233], v[0:3], v[24:27]
	v_mfma_f32_16x16x32_bf16 v[24:27], v[234:237], v[0:3], v[24:27]
	s_nop 7
	s_nop 1
	s_branch .LBB0_281
